# w_out GEMM epilogue (gate*acc) also regrouped through LDS; with w_in and MLP1 epilogues
# speedup vs baseline: 1.0079x; 1.0014x over previous
; __device__ __forceinline__ unsigned pk2(float lo, float hi) { const v2f_t f = {lo, hi}; const v2bf_t b = __builtin_convertvector(f, v2bf_t); return __builtin_bit_cast(unsigned, b); }
;     __device__ __forceinline__ void operator()(const f32x4 (&acc)[2][2][4][2], const Unit& u, int wr, int wc, int fr, int fq) const {
;     ...
;         const int mr = u.pm < 64 ? (u.pm >> 4) : 4;
;         const float* gp = gate + (size_t)mr * 6 * D + col0;
;         f32x4 gv[2][2], bv[2][2];
; #pragma unroll
;         for (int bj = 0; bj < 2; ++bj)
; #pragma unroll
;             for (int n = 0; n < 2; ++n) { gv[bj][n] = *(const f32x4*)(gp + bj * 128 + 4 * n); bv[bj][n] = bias ? *(const f32x4*)(bias + col0 + bj * 128 + 4 * n) : (f32x4){0.f, 0.f, 0.f, 0.f}; }
; #pragma unroll
;         for (int ai = 0; ai < 2; ++ai)
; #pragma unroll
;             for (int m = 0; m < 4; ++m) { bf16_t* rowp = delta + (size_t)(row0 + ai * 128 + m * 16) * D + col0;
; #pragma unroll
;                 for (int bj = 0; bj < 2; ++bj) { const f32x4 v0 = gv[bj][0] * (acc[ai][bj][m][0] + bv[bj][0]), v1 = gv[bj][1] * (acc[ai][bj][m][1] + bv[bj][1]);
;                     u32x4 w; w.x = pk2(v0[0], v0[1]); w.y = pk2(v0[2], v0[3]); w.z = pk2(v1[0], v1[1]); w.w = pk2(v1[2], v1[3]);
;                     *(u32x4*)(rowp + bj * 128) = w; } }
.LBB0_696:
	v_lshl_or_b32 v156, s24, 8, v176
	v_lshl_add_u32 v158, s22, 8, v174
	s_cmp_lt_i32 s72, 0
	v_ashrrev_i32_e32 v157, 31, v156
	s_mov_b64 s[24:25], -1
	s_cbranch_scc0 .LBB0_698
	s_ashr_i32 s11, s22, 4
	s_mul_i32 s24, s11, 6
	s_ashr_i32 s25, s24, 31
	s_lshl_b64 s[24:25], s[24:25], 11
	s_cmp_lt_i32 s22, 64
	s_cselect_b32 s25, s25, 0
	s_cselect_b32 s24, s24, 0xc000
	s_lshl_b64 s[24:25], s[24:25], 2
	s_add_u32 s24, s48, s24
	s_addc_u32 s25, s49, s25
	v_lshl_add_u64 v[134:135], v[156:157], 2, s[24:25]
	global_load_dwordx4 v[138:141], v[134:135], off offset:16
	global_load_dwordx4 v[142:145], v[134:135], off
	global_load_dwordx4 v[130:133], v[134:135], off offset:528
	s_nop 0
	global_load_dwordx4 v[134:137], v[134:135], off offset:512
	v_and_b32_e32 v157, 15, v194
	v_bfe_u32 v170, v194, 6, 2
	v_bfe_u32 v171, v194, 4, 2
	v_bfe_u32 v172, v194, 8, 1
	v_lshlrev_b32_e32 v172, 4, v172
	v_add_u32_e32 v172, v172, v157
	v_mul_u32_u24_e32 v190, 0x110, v172
	v_lshl_add_u32 v190, v170, 6, v190
	v_lshl_add_u32 v190, v171, 4, v190
	v_add_u32_e32 v190, 0x23410, v190
	v_lshrrev_b32_e32 v172, 6, v194
	v_lshl_add_u32 v172, v172, 2, v171
	v_mul_u32_u24_e32 v191, 0x110, v172
	v_lshl_add_u32 v191, v157, 4, v191
	v_add_u32_e32 v191, 0x23410, v191
	v_sub_u32_e32 v172, v158, v157
	v_lshl_add_u32 v172, v170, 2, v172
	v_add_u32_e32 v172, v172, v171
	v_lshlrev_b32_e32 v172, 12, v172
	v_and_b32_e32 v173, 0xffffff00, v156
	v_lshlrev_b32_e32 v173, 1, v173
	v_lshl_add_u32 v173, v157, 4, v173
	v_add_u32_e32 v172, v172, v173
	v_mov_b32_e32 v173, 0
	v_lshl_add_u64 v[204:205], s[2:3], 0, v[172:173]
	s_mov_b32 s25, 0
	s_waitcnt vmcnt(0)
	s_mov_b32 s24, 0x0
	v_lshl_add_u64 v[206:207], v[204:205], 0, s[24:25]
	v_pk_add_f32 v[126:127], v[126:127], 0 op_sel_hi:[1,0]
	v_pk_add_f32 v[128:129], v[128:129], 0 op_sel_hi:[1,0]
	v_pk_mul_f32 v[126:127], v[126:127], v[142:143]
	v_pk_mul_f32 v[128:129], v[128:129], v[144:145]
	v_pk_add_f32 v[122:123], v[122:123], 0 op_sel_hi:[1,0]
	v_pk_add_f32 v[124:125], v[124:125], 0 op_sel_hi:[1,0]
	v_pk_mul_f32 v[122:123], v[122:123], v[138:139]
	v_pk_mul_f32 v[124:125], v[124:125], v[140:141]
	v_cvt_pk_bf16_f32 v178, v126, v127
	v_cvt_pk_bf16_f32 v179, v128, v129
	v_cvt_pk_bf16_f32 v180, v122, v123
	v_cvt_pk_bf16_f32 v181, v124, v125
	ds_write_b128 v190, v[178:181]
	s_waitcnt lgkmcnt(0)
	s_barrier
	ds_read_b128 v[182:185], v191
	s_waitcnt lgkmcnt(0)
	global_store_dwordx4 v[206:207], v[182:185], off
	v_pk_add_f32 v[118:119], v[118:119], 0 op_sel_hi:[1,0]
	v_pk_add_f32 v[120:121], v[120:121], 0 op_sel_hi:[1,0]
	v_pk_mul_f32 v[118:119], v[118:119], v[134:135]
	v_pk_mul_f32 v[120:121], v[120:121], v[136:137]
	v_pk_add_f32 v[114:115], v[114:115], 0 op_sel_hi:[1,0]
	v_pk_add_f32 v[116:117], v[116:117], 0 op_sel_hi:[1,0]
	v_pk_mul_f32 v[114:115], v[114:115], v[130:131]
	v_pk_mul_f32 v[116:117], v[116:117], v[132:133]
	v_cvt_pk_bf16_f32 v178, v118, v119
	v_cvt_pk_bf16_f32 v179, v120, v121
	v_cvt_pk_bf16_f32 v180, v114, v115
	v_cvt_pk_bf16_f32 v181, v116, v117
	ds_write_b128 v190, v[178:181] offset:8704
	s_waitcnt lgkmcnt(0)
	s_barrier
	ds_read_b128 v[186:189], v191 offset:8704
	s_waitcnt lgkmcnt(0)
	global_store_dwordx4 v[206:207], v[186:189], off offset:256
	s_mov_b32 s24, 0x10000
	v_lshl_add_u64 v[206:207], v[204:205], 0, s[24:25]
	v_pk_add_f32 v[110:111], v[110:111], 0 op_sel_hi:[1,0]
	v_pk_add_f32 v[112:113], v[112:113], 0 op_sel_hi:[1,0]
	v_pk_mul_f32 v[110:111], v[110:111], v[142:143]
	v_pk_mul_f32 v[112:113], v[112:113], v[144:145]
	v_pk_add_f32 v[106:107], v[106:107], 0 op_sel_hi:[1,0]
	v_pk_add_f32 v[108:109], v[108:109], 0 op_sel_hi:[1,0]
	v_pk_mul_f32 v[106:107], v[106:107], v[138:139]
	v_pk_mul_f32 v[108:109], v[108:109], v[140:141]
	v_cvt_pk_bf16_f32 v178, v110, v111
	v_cvt_pk_bf16_f32 v179, v112, v113
	v_cvt_pk_bf16_f32 v180, v106, v107
	v_cvt_pk_bf16_f32 v181, v108, v109
	ds_write_b128 v190, v[178:181]
	s_waitcnt lgkmcnt(0)
	s_barrier
	ds_read_b128 v[182:185], v191
	s_waitcnt lgkmcnt(0)
	global_store_dwordx4 v[206:207], v[182:185], off
	v_pk_add_f32 v[102:103], v[102:103], 0 op_sel_hi:[1,0]
	v_pk_add_f32 v[104:105], v[104:105], 0 op_sel_hi:[1,0]
	v_pk_mul_f32 v[102:103], v[102:103], v[134:135]
	v_pk_mul_f32 v[104:105], v[104:105], v[136:137]
	v_pk_add_f32 v[98:99], v[98:99], 0 op_sel_hi:[1,0]
	v_pk_add_f32 v[100:101], v[100:101], 0 op_sel_hi:[1,0]
	v_pk_mul_f32 v[98:99], v[98:99], v[130:131]
	v_pk_mul_f32 v[100:101], v[100:101], v[132:133]
	v_cvt_pk_bf16_f32 v178, v102, v103
	v_cvt_pk_bf16_f32 v179, v104, v105
	v_cvt_pk_bf16_f32 v180, v98, v99
	v_cvt_pk_bf16_f32 v181, v100, v101
	ds_write_b128 v190, v[178:181] offset:8704
	s_waitcnt lgkmcnt(0)
	s_barrier
	ds_read_b128 v[186:189], v191 offset:8704
	s_waitcnt lgkmcnt(0)
	global_store_dwordx4 v[206:207], v[186:189], off offset:256
	s_mov_b32 s24, 0x20000
	v_lshl_add_u64 v[206:207], v[204:205], 0, s[24:25]
	v_pk_add_f32 v[94:95], v[94:95], 0 op_sel_hi:[1,0]
	v_pk_add_f32 v[96:97], v[96:97], 0 op_sel_hi:[1,0]
	v_pk_mul_f32 v[94:95], v[94:95], v[142:143]
	v_pk_mul_f32 v[96:97], v[96:97], v[144:145]
	v_pk_add_f32 v[90:91], v[90:91], 0 op_sel_hi:[1,0]
	v_pk_add_f32 v[92:93], v[92:93], 0 op_sel_hi:[1,0]
	v_pk_mul_f32 v[90:91], v[90:91], v[138:139]
	v_pk_mul_f32 v[92:93], v[92:93], v[140:141]
	v_cvt_pk_bf16_f32 v178, v94, v95
	v_cvt_pk_bf16_f32 v179, v96, v97
	v_cvt_pk_bf16_f32 v180, v90, v91
	v_cvt_pk_bf16_f32 v181, v92, v93
	ds_write_b128 v190, v[178:181]
	s_waitcnt lgkmcnt(0)
	s_barrier
; __device__ __forceinline__ unsigned pk2(float lo, float hi) { const v2f_t f = {lo, hi}; const v2bf_t b = __builtin_convertvector(f, v2bf_t); return __builtin_bit_cast(unsigned, b); }
;     __device__ __forceinline__ void operator()(const f32x4 (&acc)[2][2][4][2], const Unit& u, int wr, int wc, int fr, int fq) const {
;     ...
;         for (int ai = 0; ai < 2; ++ai)
; #pragma unroll
;             for (int m = 0; m < 4; ++m) { bf16_t* rowp = delta + (size_t)(row0 + ai * 128 + m * 16) * D + col0;
; #pragma unroll
;                 for (int bj = 0; bj < 2; ++bj) { const f32x4 v0 = gv[bj][0] * (acc[ai][bj][m][0] + bv[bj][0]), v1 = gv[bj][1] * (acc[ai][bj][m][1] + bv[bj][1]);
;                     u32x4 w; w.x = pk2(v0[0], v0[1]); w.y = pk2(v0[2], v0[3]); w.z = pk2(v1[0], v1[1]); w.w = pk2(v1[2], v1[3]);
;                     *(u32x4*)(rowp + bj * 128) = w; } }
	ds_read_b128 v[182:185], v191
	s_waitcnt lgkmcnt(0)
	global_store_dwordx4 v[206:207], v[182:185], off
	v_pk_add_f32 v[86:87], v[86:87], 0 op_sel_hi:[1,0]
	v_pk_add_f32 v[88:89], v[88:89], 0 op_sel_hi:[1,0]
	v_pk_mul_f32 v[86:87], v[86:87], v[134:135]
	v_pk_mul_f32 v[88:89], v[88:89], v[136:137]
	v_pk_add_f32 v[82:83], v[82:83], 0 op_sel_hi:[1,0]
	v_pk_add_f32 v[84:85], v[84:85], 0 op_sel_hi:[1,0]
	v_pk_mul_f32 v[82:83], v[82:83], v[130:131]
	v_pk_mul_f32 v[84:85], v[84:85], v[132:133]
	v_cvt_pk_bf16_f32 v178, v86, v87
	v_cvt_pk_bf16_f32 v179, v88, v89
	v_cvt_pk_bf16_f32 v180, v82, v83
	v_cvt_pk_bf16_f32 v181, v84, v85
	ds_write_b128 v190, v[178:181] offset:8704
	s_waitcnt lgkmcnt(0)
	s_barrier
	ds_read_b128 v[186:189], v191 offset:8704
	s_waitcnt lgkmcnt(0)
	global_store_dwordx4 v[206:207], v[186:189], off offset:256
	s_mov_b32 s24, 0x30000
	v_lshl_add_u64 v[206:207], v[204:205], 0, s[24:25]
	v_pk_add_f32 v[78:79], v[78:79], 0 op_sel_hi:[1,0]
	v_pk_add_f32 v[80:81], v[80:81], 0 op_sel_hi:[1,0]
	v_pk_mul_f32 v[78:79], v[78:79], v[142:143]
	v_pk_mul_f32 v[80:81], v[80:81], v[144:145]
	v_pk_add_f32 v[74:75], v[74:75], 0 op_sel_hi:[1,0]
	v_pk_add_f32 v[76:77], v[76:77], 0 op_sel_hi:[1,0]
	v_pk_mul_f32 v[74:75], v[74:75], v[138:139]
	v_pk_mul_f32 v[76:77], v[76:77], v[140:141]
	v_cvt_pk_bf16_f32 v178, v78, v79
	v_cvt_pk_bf16_f32 v179, v80, v81
	v_cvt_pk_bf16_f32 v180, v74, v75
	v_cvt_pk_bf16_f32 v181, v76, v77
	ds_write_b128 v190, v[178:181]
	s_waitcnt lgkmcnt(0)
	s_barrier
	ds_read_b128 v[182:185], v191
	s_waitcnt lgkmcnt(0)
	global_store_dwordx4 v[206:207], v[182:185], off
	v_pk_add_f32 v[70:71], v[70:71], 0 op_sel_hi:[1,0]
	v_pk_add_f32 v[72:73], v[72:73], 0 op_sel_hi:[1,0]
	v_pk_mul_f32 v[70:71], v[70:71], v[134:135]
	v_pk_mul_f32 v[72:73], v[72:73], v[136:137]
	v_pk_add_f32 v[66:67], v[66:67], 0 op_sel_hi:[1,0]
	v_pk_add_f32 v[68:69], v[68:69], 0 op_sel_hi:[1,0]
	v_pk_mul_f32 v[66:67], v[66:67], v[130:131]
	v_pk_mul_f32 v[68:69], v[68:69], v[132:133]
	v_cvt_pk_bf16_f32 v178, v70, v71
	v_cvt_pk_bf16_f32 v179, v72, v73
	v_cvt_pk_bf16_f32 v180, v66, v67
	v_cvt_pk_bf16_f32 v181, v68, v69
	ds_write_b128 v190, v[178:181] offset:8704
	s_waitcnt lgkmcnt(0)
	s_barrier
	ds_read_b128 v[186:189], v191 offset:8704
	s_waitcnt lgkmcnt(0)
	global_store_dwordx4 v[206:207], v[186:189], off offset:256
	s_mov_b32 s24, 0x80000
	v_lshl_add_u64 v[206:207], v[204:205], 0, s[24:25]
	v_pk_add_f32 v[60:61], v[60:61], 0 op_sel_hi:[1,0]
	v_pk_add_f32 v[62:63], v[62:63], 0 op_sel_hi:[1,0]
	v_pk_mul_f32 v[60:61], v[60:61], v[142:143]
	v_pk_mul_f32 v[62:63], v[62:63], v[144:145]
	v_pk_add_f32 v[56:57], v[56:57], 0 op_sel_hi:[1,0]
	v_pk_add_f32 v[58:59], v[58:59], 0 op_sel_hi:[1,0]
	v_pk_mul_f32 v[56:57], v[56:57], v[138:139]
	v_pk_mul_f32 v[58:59], v[58:59], v[140:141]
	v_cvt_pk_bf16_f32 v178, v60, v61
	v_cvt_pk_bf16_f32 v179, v62, v63
	v_cvt_pk_bf16_f32 v180, v56, v57
	v_cvt_pk_bf16_f32 v181, v58, v59
	ds_write_b128 v190, v[178:181]
	s_waitcnt lgkmcnt(0)
	s_barrier
	ds_read_b128 v[182:185], v191
	s_waitcnt lgkmcnt(0)
	global_store_dwordx4 v[206:207], v[182:185], off
	v_pk_add_f32 v[52:53], v[52:53], 0 op_sel_hi:[1,0]
	v_pk_add_f32 v[54:55], v[54:55], 0 op_sel_hi:[1,0]
	v_pk_mul_f32 v[52:53], v[52:53], v[134:135]
	v_pk_mul_f32 v[54:55], v[54:55], v[136:137]
	v_pk_add_f32 v[48:49], v[48:49], 0 op_sel_hi:[1,0]
	v_pk_add_f32 v[50:51], v[50:51], 0 op_sel_hi:[1,0]
	v_pk_mul_f32 v[48:49], v[48:49], v[130:131]
	v_pk_mul_f32 v[50:51], v[50:51], v[132:133]
	v_cvt_pk_bf16_f32 v178, v52, v53
	v_cvt_pk_bf16_f32 v179, v54, v55
	v_cvt_pk_bf16_f32 v180, v48, v49
	v_cvt_pk_bf16_f32 v181, v50, v51
	ds_write_b128 v190, v[178:181] offset:8704
	s_waitcnt lgkmcnt(0)
	s_barrier
	ds_read_b128 v[186:189], v191 offset:8704
	s_waitcnt lgkmcnt(0)
	global_store_dwordx4 v[206:207], v[186:189], off offset:256
	s_mov_b32 s24, 0x90000
	v_lshl_add_u64 v[206:207], v[204:205], 0, s[24:25]
	v_pk_add_f32 v[44:45], v[44:45], 0 op_sel_hi:[1,0]
	v_pk_add_f32 v[46:47], v[46:47], 0 op_sel_hi:[1,0]
	v_pk_mul_f32 v[44:45], v[44:45], v[142:143]
	v_pk_mul_f32 v[46:47], v[46:47], v[144:145]
	v_pk_add_f32 v[40:41], v[40:41], 0 op_sel_hi:[1,0]
	v_pk_add_f32 v[42:43], v[42:43], 0 op_sel_hi:[1,0]
	v_pk_mul_f32 v[40:41], v[40:41], v[138:139]
	v_pk_mul_f32 v[42:43], v[42:43], v[140:141]
	v_cvt_pk_bf16_f32 v178, v44, v45
	v_cvt_pk_bf16_f32 v179, v46, v47
	v_cvt_pk_bf16_f32 v180, v40, v41
	v_cvt_pk_bf16_f32 v181, v42, v43
	ds_write_b128 v190, v[178:181]
	s_waitcnt lgkmcnt(0)
	s_barrier
; __device__ __forceinline__ unsigned pk2(float lo, float hi) { const v2f_t f = {lo, hi}; const v2bf_t b = __builtin_convertvector(f, v2bf_t); return __builtin_bit_cast(unsigned, b); }
;     __device__ __forceinline__ void operator()(const f32x4 (&acc)[2][2][4][2], const Unit& u, int wr, int wc, int fr, int fq) const {
;     ...
;         for (int ai = 0; ai < 2; ++ai)
; #pragma unroll
;             for (int m = 0; m < 4; ++m) { bf16_t* rowp = delta + (size_t)(row0 + ai * 128 + m * 16) * D + col0;
; #pragma unroll
;                 for (int bj = 0; bj < 2; ++bj) { const f32x4 v0 = gv[bj][0] * (acc[ai][bj][m][0] + bv[bj][0]), v1 = gv[bj][1] * (acc[ai][bj][m][1] + bv[bj][1]);
;                     u32x4 w; w.x = pk2(v0[0], v0[1]); w.y = pk2(v0[2], v0[3]); w.z = pk2(v1[0], v1[1]); w.w = pk2(v1[2], v1[3]);
;                     *(u32x4*)(rowp + bj * 128) = w; } }
	ds_read_b128 v[182:185], v191
	s_waitcnt lgkmcnt(0)
	global_store_dwordx4 v[206:207], v[182:185], off
	v_pk_add_f32 v[36:37], v[36:37], 0 op_sel_hi:[1,0]
	v_pk_add_f32 v[38:39], v[38:39], 0 op_sel_hi:[1,0]
	v_pk_mul_f32 v[36:37], v[36:37], v[134:135]
	v_pk_mul_f32 v[38:39], v[38:39], v[136:137]
	v_pk_add_f32 v[32:33], v[32:33], 0 op_sel_hi:[1,0]
	v_pk_add_f32 v[34:35], v[34:35], 0 op_sel_hi:[1,0]
	v_pk_mul_f32 v[32:33], v[32:33], v[130:131]
	v_pk_mul_f32 v[34:35], v[34:35], v[132:133]
	v_cvt_pk_bf16_f32 v178, v36, v37
	v_cvt_pk_bf16_f32 v179, v38, v39
	v_cvt_pk_bf16_f32 v180, v32, v33
	v_cvt_pk_bf16_f32 v181, v34, v35
	ds_write_b128 v190, v[178:181] offset:8704
	s_waitcnt lgkmcnt(0)
	s_barrier
	ds_read_b128 v[186:189], v191 offset:8704
	s_waitcnt lgkmcnt(0)
	global_store_dwordx4 v[206:207], v[186:189], off offset:256
	s_mov_b32 s24, 0xa0000
	v_lshl_add_u64 v[206:207], v[204:205], 0, s[24:25]
	v_pk_add_f32 v[28:29], v[28:29], 0 op_sel_hi:[1,0]
	v_pk_add_f32 v[30:31], v[30:31], 0 op_sel_hi:[1,0]
	v_pk_mul_f32 v[28:29], v[28:29], v[142:143]
	v_pk_mul_f32 v[30:31], v[30:31], v[144:145]
	v_pk_add_f32 v[24:25], v[24:25], 0 op_sel_hi:[1,0]
	v_pk_add_f32 v[26:27], v[26:27], 0 op_sel_hi:[1,0]
	v_pk_mul_f32 v[24:25], v[24:25], v[138:139]
	v_pk_mul_f32 v[26:27], v[26:27], v[140:141]
	v_cvt_pk_bf16_f32 v178, v28, v29
	v_cvt_pk_bf16_f32 v179, v30, v31
	v_cvt_pk_bf16_f32 v180, v24, v25
	v_cvt_pk_bf16_f32 v181, v26, v27
	ds_write_b128 v190, v[178:181]
	s_waitcnt lgkmcnt(0)
	s_barrier
	ds_read_b128 v[182:185], v191
	s_waitcnt lgkmcnt(0)
	global_store_dwordx4 v[206:207], v[182:185], off
	v_pk_add_f32 v[20:21], v[20:21], 0 op_sel_hi:[1,0]
	v_pk_add_f32 v[22:23], v[22:23], 0 op_sel_hi:[1,0]
	v_pk_mul_f32 v[20:21], v[20:21], v[134:135]
	v_pk_mul_f32 v[22:23], v[22:23], v[136:137]
	v_pk_add_f32 v[16:17], v[16:17], 0 op_sel_hi:[1,0]
	v_pk_add_f32 v[18:19], v[18:19], 0 op_sel_hi:[1,0]
	v_pk_mul_f32 v[16:17], v[16:17], v[130:131]
	v_pk_mul_f32 v[18:19], v[18:19], v[132:133]
	v_cvt_pk_bf16_f32 v178, v20, v21
	v_cvt_pk_bf16_f32 v179, v22, v23
	v_cvt_pk_bf16_f32 v180, v16, v17
	v_cvt_pk_bf16_f32 v181, v18, v19
	ds_write_b128 v190, v[178:181] offset:8704
	s_waitcnt lgkmcnt(0)
	s_barrier
	ds_read_b128 v[186:189], v191 offset:8704
	s_waitcnt lgkmcnt(0)
	global_store_dwordx4 v[206:207], v[186:189], off offset:256
	s_mov_b32 s24, 0xb0000
	v_lshl_add_u64 v[206:207], v[204:205], 0, s[24:25]
	v_pk_add_f32 v[12:13], v[12:13], 0 op_sel_hi:[1,0]
	v_pk_add_f32 v[14:15], v[14:15], 0 op_sel_hi:[1,0]
	v_pk_mul_f32 v[12:13], v[12:13], v[142:143]
	v_pk_mul_f32 v[14:15], v[14:15], v[144:145]
	v_pk_add_f32 v[8:9], v[8:9], 0 op_sel_hi:[1,0]
	v_pk_add_f32 v[10:11], v[10:11], 0 op_sel_hi:[1,0]
	v_pk_mul_f32 v[8:9], v[8:9], v[138:139]
	v_pk_mul_f32 v[10:11], v[10:11], v[140:141]
	v_cvt_pk_bf16_f32 v178, v12, v13
	v_cvt_pk_bf16_f32 v179, v14, v15
	v_cvt_pk_bf16_f32 v180, v8, v9
	v_cvt_pk_bf16_f32 v181, v10, v11
	ds_write_b128 v190, v[178:181]
	s_waitcnt lgkmcnt(0)
	s_barrier
	ds_read_b128 v[182:185], v191
	s_waitcnt lgkmcnt(0)
	global_store_dwordx4 v[206:207], v[182:185], off
	v_pk_add_f32 v[4:5], v[4:5], 0 op_sel_hi:[1,0]
	v_pk_add_f32 v[6:7], v[6:7], 0 op_sel_hi:[1,0]
	v_pk_mul_f32 v[4:5], v[4:5], v[134:135]
	v_pk_mul_f32 v[6:7], v[6:7], v[136:137]
	v_pk_add_f32 v[0:1], v[0:1], 0 op_sel_hi:[1,0]
	v_pk_add_f32 v[2:3], v[2:3], 0 op_sel_hi:[1,0]
	v_pk_mul_f32 v[0:1], v[0:1], v[130:131]
	v_pk_mul_f32 v[2:3], v[2:3], v[132:133]
	v_cvt_pk_bf16_f32 v178, v4, v5
	v_cvt_pk_bf16_f32 v179, v6, v7
	v_cvt_pk_bf16_f32 v180, v0, v1
	v_cvt_pk_bf16_f32 v181, v2, v3
	ds_write_b128 v190, v[178:181] offset:8704
	s_waitcnt lgkmcnt(0)
	s_barrier
	ds_read_b128 v[186:189], v191 offset:8704
	s_waitcnt lgkmcnt(0)
	global_store_dwordx4 v[206:207], v[186:189], off offset:256
	s_mov_b64 s[24:25], 0
